# c11 plus LDS-DMA address generation moved from per-lane 64-bit VALU adds to scalar-base addressing (41 sites in the 8 K-loops)
# speedup vs baseline: 1.0041x; 1.0041x over previous
.LBB0_646:
	s_add_u32 s22, s90, 0xfff80800
	s_addc_u32 s23, s91, -1
	s_add_i32 s24, 0, 0x10000
	s_cmp_eq_u32 s47, 28
	s_cselect_b32 s23, s9, s23
	s_cselect_b32 s22, s21, s22
	s_cselect_b32 s27, s19, s46
	s_cselect_b32 s26, s36, s37
	s_add_i32 s64, 0, 0x14000
	v_add_u32_e32 v142, s24, v225
	v_add_u32_e32 v158, s64, v225
	ds_read_b128 v[130:133], v142
	ds_read_b128 v[134:137], v142 offset:1024
	ds_read_b128 v[138:141], v142 offset:2048
	ds_read_b128 v[142:145], v142 offset:3072
	ds_read_b128 v[146:149], v158
	ds_read_b128 v[150:153], v158 offset:1024
	ds_read_b128 v[154:157], v158 offset:2048
	ds_read_b128 v[158:161], v158 offset:3072
	s_add_i32 m0, s56, 0xc000
	ds_read_b128 v[162:165], v232
	ds_read_b128 v[166:169], v232 offset:1024
	ds_read_b128 v[170:173], v232 offset:2048
	ds_read_b128 v[174:177], v232 offset:3072
	ds_read_b128 v[178:181], v232 offset:4096
	ds_read_b128 v[182:185], v232 offset:5120
	ds_read_b128 v[186:189], v232 offset:6144
	ds_read_b128 v[190:193], v232 offset:7168
	global_load_lds_dwordx4 v200, s[90:91]
	s_add_i32 m0, s56, 0xe000
	s_nop 0
	global_load_lds_dwordx4 v202, s[90:91]
	s_waitcnt vmcnt(8)
	s_waitcnt lgkmcnt(0)
	s_setprio 1
	s_barrier
	v_mfma_f32_16x16x32_bf16 v[126:129], v[130:133], v[162:165], v[126:129]
	v_mfma_f32_16x16x32_bf16 v[122:125], v[138:141], v[162:165], v[122:125]
	v_mfma_f32_16x16x32_bf16 v[110:113], v[130:133], v[170:173], v[110:113]
	v_mfma_f32_16x16x32_bf16 v[106:109], v[138:141], v[170:173], v[106:109]
	v_mfma_f32_16x16x32_bf16 v[94:97], v[130:133], v[178:181], v[94:97]
	v_mfma_f32_16x16x32_bf16 v[90:93], v[138:141], v[178:181], v[90:93]
	v_mfma_f32_16x16x32_bf16 v[78:81], v[130:133], v[186:189], v[78:81]
	v_mfma_f32_16x16x32_bf16 v[74:77], v[138:141], v[186:189], v[74:77]
	v_mfma_f32_16x16x32_bf16 v[126:129], v[134:137], v[166:169], v[126:129]
	v_mfma_f32_16x16x32_bf16 v[122:125], v[142:145], v[166:169], v[122:125]
	v_mfma_f32_16x16x32_bf16 v[110:113], v[134:137], v[174:177], v[110:113]
	v_mfma_f32_16x16x32_bf16 v[106:109], v[142:145], v[174:177], v[106:109]
	v_mfma_f32_16x16x32_bf16 v[94:97], v[134:137], v[182:185], v[94:97]
	v_mfma_f32_16x16x32_bf16 v[90:93], v[142:145], v[182:185], v[90:93]
	v_mfma_f32_16x16x32_bf16 v[78:81], v[134:137], v[190:193], v[78:81]
	v_mfma_f32_16x16x32_bf16 v[74:77], v[142:145], v[190:193], v[74:77]
	s_setprio 0
	s_setprio 1
	v_mfma_f32_16x16x32_bf16 v[118:121], v[146:149], v[162:165], v[118:121]
	v_mfma_f32_16x16x32_bf16 v[114:117], v[154:157], v[162:165], v[114:117]
	v_mfma_f32_16x16x32_bf16 v[102:105], v[146:149], v[170:173], v[102:105]
	v_mfma_f32_16x16x32_bf16 v[98:101], v[154:157], v[170:173], v[98:101]
	v_mfma_f32_16x16x32_bf16 v[86:89], v[146:149], v[178:181], v[86:89]
	v_mfma_f32_16x16x32_bf16 v[82:85], v[154:157], v[178:181], v[82:85]
	v_mfma_f32_16x16x32_bf16 v[70:73], v[146:149], v[186:189], v[70:73]
	v_mfma_f32_16x16x32_bf16 v[66:69], v[154:157], v[186:189], v[66:69]
	v_mfma_f32_16x16x32_bf16 v[118:121], v[150:153], v[166:169], v[118:121]
	v_mfma_f32_16x16x32_bf16 v[114:117], v[158:161], v[166:169], v[114:117]
	v_mfma_f32_16x16x32_bf16 v[102:105], v[150:153], v[174:177], v[102:105]
	v_mfma_f32_16x16x32_bf16 v[98:101], v[158:161], v[174:177], v[98:101]
	v_mfma_f32_16x16x32_bf16 v[86:89], v[150:153], v[182:185], v[86:89]
	v_mfma_f32_16x16x32_bf16 v[82:85], v[158:161], v[182:185], v[82:85]
	v_mfma_f32_16x16x32_bf16 v[70:73], v[150:153], v[190:193], v[70:73]
	v_mfma_f32_16x16x32_bf16 v[66:69], v[158:161], v[190:193], v[66:69]
	s_barrier
	s_setprio 0
	s_add_i32 s24, s24, s25
	v_lshl_add_u64 v[204:205], s[26:27], 0, v[0:1]
	s_mov_b32 m0, s24
	ds_read_b128 v[162:165], v232 offset:16384
	ds_read_b128 v[166:169], v232 offset:17408
	ds_read_b128 v[170:173], v232 offset:18432
	ds_read_b128 v[174:177], v232 offset:19456
	ds_read_b128 v[178:181], v232 offset:20480
	ds_read_b128 v[182:185], v232 offset:21504
	ds_read_b128 v[186:189], v232 offset:22528
	ds_read_b128 v[190:193], v232 offset:23552
	global_load_lds_dwordx4 v[204:205], off
	s_add_i32 m0, s24, 0x2000
	s_add_u32 s50, s26, 0x80000
	v_lshl_add_u64 v[206:207], s[26:27], 0, v[198:199]
	s_addc_u32 s51, s27, 0
	s_add_i32 s24, s64, s25
	global_load_lds_dwordx4 v[206:207], off
	v_lshl_add_u64 v[208:209], s[50:51], 0, v[0:1]
	s_mov_b32 m0, s24
	v_lshl_add_u64 v[210:211], s[22:23], 0, v[196:197]
	global_load_lds_dwordx4 v[208:209], off
	s_add_i32 m0, s24, 0x2000
	s_nop 0
	global_load_lds_dwordx4 v198, s[50:51]
	v_lshl_add_u64 v[208:209], s[22:23], 0, v[194:195]
	s_mov_b32 m0, s56
	s_nop 0
	global_load_lds_dwordx4 v[208:209], off
	s_mov_b32 m0, s57
	s_nop 0
	global_load_lds_dwordx4 v[210:211], off
	s_waitcnt vmcnt(8)
	s_waitcnt lgkmcnt(0)
	s_setprio 1
	s_barrier
	v_mfma_f32_16x16x32_bf16 v[62:65], v[130:133], v[162:165], v[62:65]
	v_mfma_f32_16x16x32_bf16 v[58:61], v[138:141], v[162:165], v[58:61]
	v_mfma_f32_16x16x32_bf16 v[46:49], v[130:133], v[170:173], v[46:49]
	v_mfma_f32_16x16x32_bf16 v[42:45], v[138:141], v[170:173], v[42:45]
	v_mfma_f32_16x16x32_bf16 v[30:33], v[130:133], v[178:181], v[30:33]
	v_mfma_f32_16x16x32_bf16 v[26:29], v[138:141], v[178:181], v[26:29]
	v_mfma_f32_16x16x32_bf16 v[14:17], v[130:133], v[186:189], v[14:17]
	v_mfma_f32_16x16x32_bf16 v[10:13], v[138:141], v[186:189], v[10:13]
	v_mfma_f32_16x16x32_bf16 v[62:65], v[134:137], v[166:169], v[62:65]
	v_mfma_f32_16x16x32_bf16 v[58:61], v[142:145], v[166:169], v[58:61]
	v_mfma_f32_16x16x32_bf16 v[46:49], v[134:137], v[174:177], v[46:49]
	v_mfma_f32_16x16x32_bf16 v[42:45], v[142:145], v[174:177], v[42:45]
	v_mfma_f32_16x16x32_bf16 v[30:33], v[134:137], v[182:185], v[30:33]
	v_mfma_f32_16x16x32_bf16 v[26:29], v[142:145], v[182:185], v[26:29]
	v_mfma_f32_16x16x32_bf16 v[14:17], v[134:137], v[190:193], v[14:17]
	v_mfma_f32_16x16x32_bf16 v[10:13], v[142:145], v[190:193], v[10:13]
	s_setprio 0
	s_setprio 1
	v_mfma_f32_16x16x32_bf16 v[54:57], v[146:149], v[162:165], v[54:57]
	v_mfma_f32_16x16x32_bf16 v[50:53], v[154:157], v[162:165], v[50:53]
	v_mfma_f32_16x16x32_bf16 v[38:41], v[146:149], v[170:173], v[38:41]
	v_mfma_f32_16x16x32_bf16 v[34:37], v[154:157], v[170:173], v[34:37]
	v_mfma_f32_16x16x32_bf16 v[22:25], v[146:149], v[178:181], v[22:25]
	v_mfma_f32_16x16x32_bf16 v[18:21], v[154:157], v[178:181], v[18:21]
	v_mfma_f32_16x16x32_bf16 v[6:9], v[146:149], v[186:189], v[6:9]
	v_mfma_f32_16x16x32_bf16 v[2:5], v[154:157], v[186:189], v[2:5]
	v_mfma_f32_16x16x32_bf16 v[54:57], v[150:153], v[166:169], v[54:57]
	v_mfma_f32_16x16x32_bf16 v[50:53], v[158:161], v[166:169], v[50:53]
	v_mfma_f32_16x16x32_bf16 v[38:41], v[150:153], v[174:177], v[38:41]
	v_mfma_f32_16x16x32_bf16 v[34:37], v[158:161], v[174:177], v[34:37]
	v_mfma_f32_16x16x32_bf16 v[22:25], v[150:153], v[182:185], v[22:25]
	v_mfma_f32_16x16x32_bf16 v[18:21], v[158:161], v[182:185], v[18:21]
	v_mfma_f32_16x16x32_bf16 v[6:9], v[150:153], v[190:193], v[6:9]
	v_mfma_f32_16x16x32_bf16 v[2:5], v[158:161], v[190:193], v[2:5]
	s_barrier
	s_setprio 0
	s_add_i32 s24, 0, 0x18000
	s_add_i32 s50, 0, 0x1c000
	v_add_u32_e32 v142, s24, v225
	v_add_u32_e32 v158, s50, v225
	ds_read_b128 v[130:133], v142
	ds_read_b128 v[134:137], v142 offset:1024
	ds_read_b128 v[138:141], v142 offset:2048
	ds_read_b128 v[142:145], v142 offset:3072
	ds_read_b128 v[146:149], v158
	ds_read_b128 v[150:153], v158 offset:1024
	ds_read_b128 v[154:157], v158 offset:2048
	ds_read_b128 v[158:161], v158 offset:3072
	s_add_u32 s22, s22, 0x80000
	s_addc_u32 s23, s23, 0
	s_mov_b32 m0, s60
	ds_read_b128 v[162:165], v232 offset:32768
	ds_read_b128 v[166:169], v232 offset:33792
	ds_read_b128 v[170:173], v232 offset:34816
	ds_read_b128 v[174:177], v232 offset:35840
	ds_read_b128 v[178:181], v232 offset:36864
	ds_read_b128 v[182:185], v232 offset:37888
	ds_read_b128 v[186:189], v232 offset:38912
	ds_read_b128 v[190:193], v232 offset:39936
	global_load_lds_dwordx4 v194, s[22:23]
	s_mov_b32 m0, s61
	s_nop 0
	global_load_lds_dwordx4 v196, s[22:23]
	s_waitcnt vmcnt(8)
	s_waitcnt lgkmcnt(0)
	s_setprio 1
	s_barrier
	v_mfma_f32_16x16x32_bf16 v[126:129], v[130:133], v[162:165], v[126:129]
	v_mfma_f32_16x16x32_bf16 v[122:125], v[138:141], v[162:165], v[122:125]
	v_mfma_f32_16x16x32_bf16 v[110:113], v[130:133], v[170:173], v[110:113]
	v_mfma_f32_16x16x32_bf16 v[106:109], v[138:141], v[170:173], v[106:109]
	v_mfma_f32_16x16x32_bf16 v[94:97], v[130:133], v[178:181], v[94:97]
	v_mfma_f32_16x16x32_bf16 v[90:93], v[138:141], v[178:181], v[90:93]
	v_mfma_f32_16x16x32_bf16 v[78:81], v[130:133], v[186:189], v[78:81]
	v_mfma_f32_16x16x32_bf16 v[74:77], v[138:141], v[186:189], v[74:77]
	v_mfma_f32_16x16x32_bf16 v[126:129], v[134:137], v[166:169], v[126:129]
	v_mfma_f32_16x16x32_bf16 v[122:125], v[142:145], v[166:169], v[122:125]
	v_mfma_f32_16x16x32_bf16 v[110:113], v[134:137], v[174:177], v[110:113]
	v_mfma_f32_16x16x32_bf16 v[106:109], v[142:145], v[174:177], v[106:109]
	v_mfma_f32_16x16x32_bf16 v[94:97], v[134:137], v[182:185], v[94:97]
	v_mfma_f32_16x16x32_bf16 v[90:93], v[142:145], v[182:185], v[90:93]
	v_mfma_f32_16x16x32_bf16 v[78:81], v[134:137], v[190:193], v[78:81]
	v_mfma_f32_16x16x32_bf16 v[74:77], v[142:145], v[190:193], v[74:77]
	s_setprio 0
	s_setprio 1
	v_mfma_f32_16x16x32_bf16 v[118:121], v[146:149], v[162:165], v[118:121]
	v_mfma_f32_16x16x32_bf16 v[114:117], v[154:157], v[162:165], v[114:117]
	v_mfma_f32_16x16x32_bf16 v[102:105], v[146:149], v[170:173], v[102:105]
	v_mfma_f32_16x16x32_bf16 v[98:101], v[154:157], v[170:173], v[98:101]
	v_mfma_f32_16x16x32_bf16 v[86:89], v[146:149], v[178:181], v[86:89]
	v_mfma_f32_16x16x32_bf16 v[82:85], v[154:157], v[178:181], v[82:85]
	v_mfma_f32_16x16x32_bf16 v[70:73], v[146:149], v[186:189], v[70:73]
	v_mfma_f32_16x16x32_bf16 v[66:69], v[154:157], v[186:189], v[66:69]
	v_mfma_f32_16x16x32_bf16 v[118:121], v[150:153], v[166:169], v[118:121]
	v_mfma_f32_16x16x32_bf16 v[114:117], v[158:161], v[166:169], v[114:117]
	v_mfma_f32_16x16x32_bf16 v[102:105], v[150:153], v[174:177], v[102:105]
	v_mfma_f32_16x16x32_bf16 v[98:101], v[158:161], v[174:177], v[98:101]
	v_mfma_f32_16x16x32_bf16 v[86:89], v[150:153], v[182:185], v[86:89]
	v_mfma_f32_16x16x32_bf16 v[82:85], v[158:161], v[182:185], v[82:85]
	v_mfma_f32_16x16x32_bf16 v[70:73], v[150:153], v[190:193], v[70:73]
	v_mfma_f32_16x16x32_bf16 v[66:69], v[158:161], v[190:193], v[66:69]
	s_barrier
	s_setprio 0
	s_add_i32 s22, s24, s25
	v_lshl_add_u64 v[204:205], v[204:205], 0, s[34:35]
	s_mov_b32 m0, s22
	ds_read_b128 v[162:165], v232 offset:49152
	ds_read_b128 v[166:169], v232 offset:50176
	ds_read_b128 v[170:173], v232 offset:51200
	ds_read_b128 v[174:177], v232 offset:52224
	ds_read_b128 v[178:181], v232 offset:53248
	ds_read_b128 v[182:185], v232 offset:54272
	ds_read_b128 v[186:189], v232 offset:55296
	ds_read_b128 v[190:193], v232 offset:56320
	global_load_lds_dwordx4 v[204:205], off
	s_add_i32 m0, s22, 0x2000
	s_add_u32 s22, s26, 0x80080
	v_lshl_add_u64 v[204:205], v[206:207], 0, s[34:35]
	s_addc_u32 s23, s27, 0
	s_add_i32 s24, s50, s25
	global_load_lds_dwordx4 v[204:205], off
	v_lshl_add_u64 v[204:205], s[22:23], 0, v[0:1]
	s_mov_b32 m0, s24
	s_nop 0
	global_load_lds_dwordx4 v[204:205], off
	s_add_i32 m0, s24, 0x2000
	s_nop 0
	global_load_lds_dwordx4 v198, s[22:23]
	v_lshl_add_u64 v[204:205], v[208:209], 0, s[100:101]
	s_mov_b32 m0, s75
	s_nop 0
	global_load_lds_dwordx4 v[204:205], off
	v_lshl_add_u64 v[204:205], v[210:211], 0, s[100:101]
	s_mov_b32 m0, s76
	s_nop 0
	global_load_lds_dwordx4 v[204:205], off
	s_waitcnt vmcnt(8)
	s_waitcnt lgkmcnt(0)
	s_setprio 1
	s_barrier
	v_mfma_f32_16x16x32_bf16 v[62:65], v[130:133], v[162:165], v[62:65]
	v_mfma_f32_16x16x32_bf16 v[58:61], v[138:141], v[162:165], v[58:61]
	v_mfma_f32_16x16x32_bf16 v[46:49], v[130:133], v[170:173], v[46:49]
	v_mfma_f32_16x16x32_bf16 v[42:45], v[138:141], v[170:173], v[42:45]
	v_mfma_f32_16x16x32_bf16 v[30:33], v[130:133], v[178:181], v[30:33]
	v_mfma_f32_16x16x32_bf16 v[26:29], v[138:141], v[178:181], v[26:29]
	v_mfma_f32_16x16x32_bf16 v[14:17], v[130:133], v[186:189], v[14:17]
	v_mfma_f32_16x16x32_bf16 v[10:13], v[138:141], v[186:189], v[10:13]
	v_mfma_f32_16x16x32_bf16 v[62:65], v[134:137], v[166:169], v[62:65]
	v_mfma_f32_16x16x32_bf16 v[58:61], v[142:145], v[166:169], v[58:61]
	v_mfma_f32_16x16x32_bf16 v[46:49], v[134:137], v[174:177], v[46:49]
	v_mfma_f32_16x16x32_bf16 v[42:45], v[142:145], v[174:177], v[42:45]
	v_mfma_f32_16x16x32_bf16 v[30:33], v[134:137], v[182:185], v[30:33]
	v_mfma_f32_16x16x32_bf16 v[26:29], v[142:145], v[182:185], v[26:29]
	v_mfma_f32_16x16x32_bf16 v[14:17], v[134:137], v[190:193], v[14:17]
	v_mfma_f32_16x16x32_bf16 v[10:13], v[142:145], v[190:193], v[10:13]
	s_setprio 0
	s_setprio 1
	v_mfma_f32_16x16x32_bf16 v[54:57], v[146:149], v[162:165], v[54:57]
	v_mfma_f32_16x16x32_bf16 v[50:53], v[154:157], v[162:165], v[50:53]
	v_mfma_f32_16x16x32_bf16 v[38:41], v[146:149], v[170:173], v[38:41]
	v_mfma_f32_16x16x32_bf16 v[34:37], v[154:157], v[170:173], v[34:37]
	v_mfma_f32_16x16x32_bf16 v[22:25], v[146:149], v[178:181], v[22:25]
	v_mfma_f32_16x16x32_bf16 v[18:21], v[154:157], v[178:181], v[18:21]
	v_mfma_f32_16x16x32_bf16 v[6:9], v[146:149], v[186:189], v[6:9]
	v_mfma_f32_16x16x32_bf16 v[2:5], v[154:157], v[186:189], v[2:5]
	v_mfma_f32_16x16x32_bf16 v[54:57], v[150:153], v[166:169], v[54:57]
	v_mfma_f32_16x16x32_bf16 v[50:53], v[158:161], v[166:169], v[50:53]
	v_mfma_f32_16x16x32_bf16 v[38:41], v[150:153], v[174:177], v[38:41]
	v_mfma_f32_16x16x32_bf16 v[34:37], v[158:161], v[174:177], v[34:37]
	v_mfma_f32_16x16x32_bf16 v[22:25], v[150:153], v[182:185], v[22:25]
	v_mfma_f32_16x16x32_bf16 v[18:21], v[158:161], v[182:185], v[18:21]
	v_mfma_f32_16x16x32_bf16 v[6:9], v[150:153], v[190:193], v[6:9]
	v_mfma_f32_16x16x32_bf16 v[2:5], v[158:161], v[190:193], v[2:5]
	s_barrier
	s_setprio 0
	s_add_i32 s47, s47, 2
	s_add_u32 s90, s90, 0x1000
	s_addc_u32 s91, s91, 0
	s_add_u32 s37, s37, 0x100
	s_addc_u32 s46, s46, 0
	s_cmp_gt_u32 s47, 29
	s_cbranch_scc0 .LBB0_646
	s_and_b64 vcc, exec, s[14:15]
	s_cbranch_vccz .LBB0_649
	s_barrier

.LBB0_882:
	s_add_u32 s22, s46, 0xffe00800
	s_addc_u32 s23, s47, -1
	s_add_i32 s24, 0, 0x10000
	s_cmpk_eq_i32 s39, 0x7c
	s_cselect_b32 s23, s13, s23
	s_cselect_b32 s22, s19, s22
	s_cselect_b32 s27, s11, s37
	s_cselect_b32 s26, s21, s36
	s_add_i32 s64, 0, 0x14000
	v_add_u32_e32 v142, s24, v209
	v_add_u32_e32 v168, s64, v209
	ds_read_b128 v[130:133], v142
	ds_read_b128 v[134:137], v142 offset:1024
	ds_read_b128 v[138:141], v142 offset:2048
	ds_read_b128 v[142:145], v142 offset:3072
	ds_read_b128 v[146:149], v168
	ds_read_b128 v[150:153], v168 offset:1024
	ds_read_b128 v[154:157], v168 offset:2048
	ds_read_b128 v[168:171], v168 offset:3072
	s_add_i32 m0, s60, 0xc000
	ds_read_b128 v[172:175], v224
	ds_read_b128 v[176:179], v224 offset:1024
	ds_read_b128 v[180:183], v224 offset:2048
	ds_read_b128 v[184:187], v224 offset:3072
	ds_read_b128 v[188:191], v224 offset:4096
	ds_read_b128 v[192:195], v224 offset:5120
	ds_read_b128 v[196:199], v224 offset:6144
	ds_read_b128 v[200:203], v224 offset:7168
	global_load_lds_dwordx4 v164, s[46:47]
	s_add_i32 m0, s60, 0xe000
	s_nop 0
	global_load_lds_dwordx4 v166, s[46:47]
	s_waitcnt vmcnt(8)
	s_waitcnt lgkmcnt(0)
	s_setprio 1
	s_barrier
	v_mfma_f32_16x16x32_bf16 v[126:129], v[130:133], v[172:175], v[126:129]
	v_mfma_f32_16x16x32_bf16 v[122:125], v[138:141], v[172:175], v[122:125]
	v_mfma_f32_16x16x32_bf16 v[110:113], v[130:133], v[180:183], v[110:113]
	v_mfma_f32_16x16x32_bf16 v[106:109], v[138:141], v[180:183], v[106:109]
	v_mfma_f32_16x16x32_bf16 v[94:97], v[130:133], v[188:191], v[94:97]
	v_mfma_f32_16x16x32_bf16 v[90:93], v[138:141], v[188:191], v[90:93]
	v_mfma_f32_16x16x32_bf16 v[78:81], v[130:133], v[196:199], v[78:81]
	v_mfma_f32_16x16x32_bf16 v[74:77], v[138:141], v[196:199], v[74:77]
	v_mfma_f32_16x16x32_bf16 v[126:129], v[134:137], v[176:179], v[126:129]
	v_mfma_f32_16x16x32_bf16 v[122:125], v[142:145], v[176:179], v[122:125]
	v_mfma_f32_16x16x32_bf16 v[110:113], v[134:137], v[184:187], v[110:113]
	v_mfma_f32_16x16x32_bf16 v[106:109], v[142:145], v[184:187], v[106:109]
	v_mfma_f32_16x16x32_bf16 v[94:97], v[134:137], v[192:195], v[94:97]
	v_mfma_f32_16x16x32_bf16 v[90:93], v[142:145], v[192:195], v[90:93]
	v_mfma_f32_16x16x32_bf16 v[78:81], v[134:137], v[200:203], v[78:81]
	v_mfma_f32_16x16x32_bf16 v[74:77], v[142:145], v[200:203], v[74:77]
	s_setprio 0
	s_setprio 1
	v_mfma_f32_16x16x32_bf16 v[118:121], v[146:149], v[172:175], v[118:121]
	v_mfma_f32_16x16x32_bf16 v[114:117], v[154:157], v[172:175], v[114:117]
	v_mfma_f32_16x16x32_bf16 v[102:105], v[146:149], v[180:183], v[102:105]
	v_mfma_f32_16x16x32_bf16 v[98:101], v[154:157], v[180:183], v[98:101]
	v_mfma_f32_16x16x32_bf16 v[86:89], v[146:149], v[188:191], v[86:89]
	v_mfma_f32_16x16x32_bf16 v[82:85], v[154:157], v[188:191], v[82:85]
	v_mfma_f32_16x16x32_bf16 v[70:73], v[146:149], v[196:199], v[70:73]
	v_mfma_f32_16x16x32_bf16 v[66:69], v[154:157], v[196:199], v[66:69]
	v_mfma_f32_16x16x32_bf16 v[118:121], v[150:153], v[176:179], v[118:121]
	v_mfma_f32_16x16x32_bf16 v[114:117], v[168:171], v[176:179], v[114:117]
	v_mfma_f32_16x16x32_bf16 v[102:105], v[150:153], v[184:187], v[102:105]
	v_mfma_f32_16x16x32_bf16 v[98:101], v[168:171], v[184:187], v[98:101]
	v_mfma_f32_16x16x32_bf16 v[86:89], v[150:153], v[192:195], v[86:89]
	v_mfma_f32_16x16x32_bf16 v[82:85], v[168:171], v[192:195], v[82:85]
	v_mfma_f32_16x16x32_bf16 v[70:73], v[150:153], v[200:203], v[70:73]
	v_mfma_f32_16x16x32_bf16 v[66:69], v[168:171], v[200:203], v[66:69]
	s_barrier
	s_setprio 0
	s_add_i32 s24, s24, s57
	v_lshl_add_u64 v[204:205], s[26:27], 0, v[0:1]
	s_mov_b32 m0, s24
	ds_read_b128 v[172:175], v224 offset:16384
	ds_read_b128 v[176:179], v224 offset:17408
	ds_read_b128 v[180:183], v224 offset:18432
	ds_read_b128 v[184:187], v224 offset:19456
	ds_read_b128 v[188:191], v224 offset:20480
	ds_read_b128 v[192:195], v224 offset:21504
	ds_read_b128 v[196:199], v224 offset:22528
	ds_read_b128 v[200:203], v224 offset:23552
	global_load_lds_dwordx4 v[204:205], off
	s_add_i32 m0, s24, 0x2000
	s_add_u32 s62, s26, 0x200000
	v_lshl_add_u64 v[214:215], s[26:27], 0, v[162:163]
	s_addc_u32 s63, s27, 0
	s_add_i32 s24, s64, s57
	global_load_lds_dwordx4 v[214:215], off
	v_lshl_add_u64 v[230:231], s[62:63], 0, v[0:1]
	s_mov_b32 m0, s24
	v_lshl_add_u64 v[232:233], s[22:23], 0, v[160:161]
	global_load_lds_dwordx4 v[230:231], off
	s_add_i32 m0, s24, 0x2000
	s_nop 0
	global_load_lds_dwordx4 v162, s[62:63]
	v_lshl_add_u64 v[230:231], s[22:23], 0, v[158:159]
	s_mov_b32 m0, s60
	s_nop 0
	global_load_lds_dwordx4 v[230:231], off
	s_mov_b32 m0, s61
	s_nop 0
	global_load_lds_dwordx4 v[232:233], off
	s_waitcnt vmcnt(8)
	s_waitcnt lgkmcnt(0)
	s_setprio 1
	s_barrier
	v_mfma_f32_16x16x32_bf16 v[62:65], v[130:133], v[172:175], v[62:65]
	v_mfma_f32_16x16x32_bf16 v[58:61], v[138:141], v[172:175], v[58:61]
	v_mfma_f32_16x16x32_bf16 v[46:49], v[130:133], v[180:183], v[46:49]
	v_mfma_f32_16x16x32_bf16 v[42:45], v[138:141], v[180:183], v[42:45]
	v_mfma_f32_16x16x32_bf16 v[30:33], v[130:133], v[188:191], v[30:33]
	v_mfma_f32_16x16x32_bf16 v[26:29], v[138:141], v[188:191], v[26:29]
	v_mfma_f32_16x16x32_bf16 v[14:17], v[130:133], v[196:199], v[14:17]
	v_mfma_f32_16x16x32_bf16 v[10:13], v[138:141], v[196:199], v[10:13]
	v_mfma_f32_16x16x32_bf16 v[62:65], v[134:137], v[176:179], v[62:65]
	v_mfma_f32_16x16x32_bf16 v[58:61], v[142:145], v[176:179], v[58:61]
	v_mfma_f32_16x16x32_bf16 v[46:49], v[134:137], v[184:187], v[46:49]
	v_mfma_f32_16x16x32_bf16 v[42:45], v[142:145], v[184:187], v[42:45]
	v_mfma_f32_16x16x32_bf16 v[30:33], v[134:137], v[192:195], v[30:33]
	v_mfma_f32_16x16x32_bf16 v[26:29], v[142:145], v[192:195], v[26:29]
	v_mfma_f32_16x16x32_bf16 v[14:17], v[134:137], v[200:203], v[14:17]
	v_mfma_f32_16x16x32_bf16 v[10:13], v[142:145], v[200:203], v[10:13]
	s_setprio 0
	s_setprio 1
	v_mfma_f32_16x16x32_bf16 v[54:57], v[146:149], v[172:175], v[54:57]
	v_mfma_f32_16x16x32_bf16 v[50:53], v[154:157], v[172:175], v[50:53]
	v_mfma_f32_16x16x32_bf16 v[38:41], v[146:149], v[180:183], v[38:41]
	v_mfma_f32_16x16x32_bf16 v[34:37], v[154:157], v[180:183], v[34:37]
	v_mfma_f32_16x16x32_bf16 v[22:25], v[146:149], v[188:191], v[22:25]
	v_mfma_f32_16x16x32_bf16 v[18:21], v[154:157], v[188:191], v[18:21]
	v_mfma_f32_16x16x32_bf16 v[6:9], v[146:149], v[196:199], v[6:9]
	v_mfma_f32_16x16x32_bf16 v[2:5], v[154:157], v[196:199], v[2:5]
	v_mfma_f32_16x16x32_bf16 v[54:57], v[150:153], v[176:179], v[54:57]
	v_mfma_f32_16x16x32_bf16 v[50:53], v[168:171], v[176:179], v[50:53]
	v_mfma_f32_16x16x32_bf16 v[38:41], v[150:153], v[184:187], v[38:41]
	v_mfma_f32_16x16x32_bf16 v[34:37], v[168:171], v[184:187], v[34:37]
	v_mfma_f32_16x16x32_bf16 v[22:25], v[150:153], v[192:195], v[22:25]
	v_mfma_f32_16x16x32_bf16 v[18:21], v[168:171], v[192:195], v[18:21]
	v_mfma_f32_16x16x32_bf16 v[6:9], v[150:153], v[200:203], v[6:9]
	v_mfma_f32_16x16x32_bf16 v[2:5], v[168:171], v[200:203], v[2:5]
	s_barrier
	s_setprio 0
	s_add_i32 s24, 0, 0x18000
	s_add_i32 s62, 0, 0x1c000
	v_add_u32_e32 v142, s24, v209
	v_add_u32_e32 v168, s62, v209
	ds_read_b128 v[130:133], v142
	ds_read_b128 v[134:137], v142 offset:1024
	ds_read_b128 v[138:141], v142 offset:2048
	ds_read_b128 v[142:145], v142 offset:3072
	ds_read_b128 v[146:149], v168
	ds_read_b128 v[150:153], v168 offset:1024
	ds_read_b128 v[154:157], v168 offset:2048
	ds_read_b128 v[168:171], v168 offset:3072
	s_add_u32 s22, s22, 0x200000
	s_addc_u32 s23, s23, 0
	s_mov_b32 m0, s76
	ds_read_b128 v[172:175], v224 offset:32768
	ds_read_b128 v[176:179], v224 offset:33792
	ds_read_b128 v[180:183], v224 offset:34816
	ds_read_b128 v[184:187], v224 offset:35840
	ds_read_b128 v[188:191], v224 offset:36864
	ds_read_b128 v[192:195], v224 offset:37888
	ds_read_b128 v[196:199], v224 offset:38912
	ds_read_b128 v[200:203], v224 offset:39936
	global_load_lds_dwordx4 v158, s[22:23]
	s_mov_b32 m0, s77
	s_nop 0
	global_load_lds_dwordx4 v160, s[22:23]
	s_waitcnt vmcnt(8)
	s_waitcnt lgkmcnt(0)
	s_setprio 1
	s_barrier
	v_mfma_f32_16x16x32_bf16 v[126:129], v[130:133], v[172:175], v[126:129]
	v_mfma_f32_16x16x32_bf16 v[122:125], v[138:141], v[172:175], v[122:125]
	v_mfma_f32_16x16x32_bf16 v[110:113], v[130:133], v[180:183], v[110:113]
	v_mfma_f32_16x16x32_bf16 v[106:109], v[138:141], v[180:183], v[106:109]
	v_mfma_f32_16x16x32_bf16 v[94:97], v[130:133], v[188:191], v[94:97]
	v_mfma_f32_16x16x32_bf16 v[90:93], v[138:141], v[188:191], v[90:93]
	v_mfma_f32_16x16x32_bf16 v[78:81], v[130:133], v[196:199], v[78:81]
	v_mfma_f32_16x16x32_bf16 v[74:77], v[138:141], v[196:199], v[74:77]
	v_mfma_f32_16x16x32_bf16 v[126:129], v[134:137], v[176:179], v[126:129]
	v_mfma_f32_16x16x32_bf16 v[122:125], v[142:145], v[176:179], v[122:125]
	v_mfma_f32_16x16x32_bf16 v[110:113], v[134:137], v[184:187], v[110:113]
	v_mfma_f32_16x16x32_bf16 v[106:109], v[142:145], v[184:187], v[106:109]
	v_mfma_f32_16x16x32_bf16 v[94:97], v[134:137], v[192:195], v[94:97]
	v_mfma_f32_16x16x32_bf16 v[90:93], v[142:145], v[192:195], v[90:93]
	v_mfma_f32_16x16x32_bf16 v[78:81], v[134:137], v[200:203], v[78:81]
	v_mfma_f32_16x16x32_bf16 v[74:77], v[142:145], v[200:203], v[74:77]
	s_setprio 0
	s_setprio 1
	v_mfma_f32_16x16x32_bf16 v[118:121], v[146:149], v[172:175], v[118:121]
	v_mfma_f32_16x16x32_bf16 v[114:117], v[154:157], v[172:175], v[114:117]
	v_mfma_f32_16x16x32_bf16 v[102:105], v[146:149], v[180:183], v[102:105]
	v_mfma_f32_16x16x32_bf16 v[98:101], v[154:157], v[180:183], v[98:101]
	v_mfma_f32_16x16x32_bf16 v[86:89], v[146:149], v[188:191], v[86:89]
	v_mfma_f32_16x16x32_bf16 v[82:85], v[154:157], v[188:191], v[82:85]
	v_mfma_f32_16x16x32_bf16 v[70:73], v[146:149], v[196:199], v[70:73]
	v_mfma_f32_16x16x32_bf16 v[66:69], v[154:157], v[196:199], v[66:69]
	v_mfma_f32_16x16x32_bf16 v[118:121], v[150:153], v[176:179], v[118:121]
	v_mfma_f32_16x16x32_bf16 v[114:117], v[168:171], v[176:179], v[114:117]
	v_mfma_f32_16x16x32_bf16 v[102:105], v[150:153], v[184:187], v[102:105]
	v_mfma_f32_16x16x32_bf16 v[98:101], v[168:171], v[184:187], v[98:101]
	v_mfma_f32_16x16x32_bf16 v[86:89], v[150:153], v[192:195], v[86:89]
	v_mfma_f32_16x16x32_bf16 v[82:85], v[168:171], v[192:195], v[82:85]
	v_mfma_f32_16x16x32_bf16 v[70:73], v[150:153], v[200:203], v[70:73]
	v_mfma_f32_16x16x32_bf16 v[66:69], v[168:171], v[200:203], v[66:69]
	s_barrier
	s_setprio 0
	s_add_i32 s22, s24, s57
	v_lshl_add_u64 v[204:205], v[204:205], 0, s[34:35]
	s_mov_b32 m0, s22
	ds_read_b128 v[172:175], v224 offset:49152
	ds_read_b128 v[176:179], v224 offset:50176
	ds_read_b128 v[180:183], v224 offset:51200
	ds_read_b128 v[184:187], v224 offset:52224
	ds_read_b128 v[188:191], v224 offset:53248
	ds_read_b128 v[192:195], v224 offset:54272
	ds_read_b128 v[196:199], v224 offset:55296
	ds_read_b128 v[200:203], v224 offset:56320
	global_load_lds_dwordx4 v[204:205], off
	s_add_i32 m0, s22, 0x2000
	s_add_u32 s22, s26, 0x200080
	v_lshl_add_u64 v[204:205], v[214:215], 0, s[34:35]
	s_addc_u32 s23, s27, 0
	s_add_i32 s24, s62, s57
	global_load_lds_dwordx4 v[204:205], off
	v_lshl_add_u64 v[204:205], s[22:23], 0, v[0:1]
	s_mov_b32 m0, s24
	s_nop 0
	global_load_lds_dwordx4 v[204:205], off
	s_add_i32 m0, s24, 0x2000
	s_nop 0
	global_load_lds_dwordx4 v162, s[22:23]
	v_lshl_add_u64 v[204:205], v[230:231], 0, s[100:101]
	s_mov_b32 m0, s81
	s_nop 0
	global_load_lds_dwordx4 v[204:205], off
	v_lshl_add_u64 v[204:205], v[232:233], 0, s[100:101]
	s_mov_b32 m0, s82
	s_nop 0
	global_load_lds_dwordx4 v[204:205], off
	s_waitcnt vmcnt(8)
	s_waitcnt lgkmcnt(0)
	s_setprio 1
	s_barrier
	v_mfma_f32_16x16x32_bf16 v[62:65], v[130:133], v[172:175], v[62:65]
	v_mfma_f32_16x16x32_bf16 v[58:61], v[138:141], v[172:175], v[58:61]
	v_mfma_f32_16x16x32_bf16 v[46:49], v[130:133], v[180:183], v[46:49]
	v_mfma_f32_16x16x32_bf16 v[42:45], v[138:141], v[180:183], v[42:45]
	v_mfma_f32_16x16x32_bf16 v[30:33], v[130:133], v[188:191], v[30:33]
	v_mfma_f32_16x16x32_bf16 v[26:29], v[138:141], v[188:191], v[26:29]
	v_mfma_f32_16x16x32_bf16 v[14:17], v[130:133], v[196:199], v[14:17]
	v_mfma_f32_16x16x32_bf16 v[10:13], v[138:141], v[196:199], v[10:13]
	v_mfma_f32_16x16x32_bf16 v[62:65], v[134:137], v[176:179], v[62:65]
	v_mfma_f32_16x16x32_bf16 v[58:61], v[142:145], v[176:179], v[58:61]
	v_mfma_f32_16x16x32_bf16 v[46:49], v[134:137], v[184:187], v[46:49]
	v_mfma_f32_16x16x32_bf16 v[42:45], v[142:145], v[184:187], v[42:45]
	v_mfma_f32_16x16x32_bf16 v[30:33], v[134:137], v[192:195], v[30:33]
	v_mfma_f32_16x16x32_bf16 v[26:29], v[142:145], v[192:195], v[26:29]
	v_mfma_f32_16x16x32_bf16 v[14:17], v[134:137], v[200:203], v[14:17]
	v_mfma_f32_16x16x32_bf16 v[10:13], v[142:145], v[200:203], v[10:13]
	s_setprio 0
	s_setprio 1
	v_mfma_f32_16x16x32_bf16 v[54:57], v[146:149], v[172:175], v[54:57]
	v_mfma_f32_16x16x32_bf16 v[50:53], v[154:157], v[172:175], v[50:53]
	v_mfma_f32_16x16x32_bf16 v[38:41], v[146:149], v[180:183], v[38:41]
	v_mfma_f32_16x16x32_bf16 v[34:37], v[154:157], v[180:183], v[34:37]
	v_mfma_f32_16x16x32_bf16 v[22:25], v[146:149], v[188:191], v[22:25]
	v_mfma_f32_16x16x32_bf16 v[18:21], v[154:157], v[188:191], v[18:21]
	v_mfma_f32_16x16x32_bf16 v[6:9], v[146:149], v[196:199], v[6:9]
	v_mfma_f32_16x16x32_bf16 v[2:5], v[154:157], v[196:199], v[2:5]
	v_mfma_f32_16x16x32_bf16 v[54:57], v[150:153], v[176:179], v[54:57]
	v_mfma_f32_16x16x32_bf16 v[50:53], v[168:171], v[176:179], v[50:53]
	v_mfma_f32_16x16x32_bf16 v[38:41], v[150:153], v[184:187], v[38:41]
	v_mfma_f32_16x16x32_bf16 v[34:37], v[168:171], v[184:187], v[34:37]
	v_mfma_f32_16x16x32_bf16 v[22:25], v[150:153], v[192:195], v[22:25]
	v_mfma_f32_16x16x32_bf16 v[18:21], v[168:171], v[192:195], v[18:21]
	v_mfma_f32_16x16x32_bf16 v[6:9], v[150:153], v[200:203], v[6:9]
	v_mfma_f32_16x16x32_bf16 v[2:5], v[168:171], v[200:203], v[2:5]
	s_barrier
	s_setprio 0
	s_add_i32 s39, s39, 2
	s_add_u32 s46, s46, 0x1000
	s_addc_u32 s47, s47, 0
	s_add_u32 s36, s36, 0x100
	s_addc_u32 s37, s37, 0
	s_cmpk_gt_u32 s39, 0x7d
	s_cbranch_scc0 .LBB0_882
	s_and_b64 vcc, exec, s[8:9]
	s_cbranch_vccz .LBB0_885
	s_barrier

.LBB0_1004:
	s_add_u32 s22, s46, 0xffe00800
	s_addc_u32 s23, s47, -1
	s_add_i32 s24, 0, 0x10000
	s_cmpk_eq_i32 s48, 0x7c
	s_cselect_b32 s23, s3, s23
	s_cselect_b32 s22, s15, s22
	s_cselect_b32 s27, s13, s37
	s_cselect_b32 s26, s21, s36
	s_add_i32 s49, 0, 0x14000
	v_add_u32_e32 v142, s24, v177
	v_add_u32_e32 v168, s49, v177
	ds_read_b128 v[130:133], v142
	ds_read_b128 v[134:137], v142 offset:1024
	ds_read_b128 v[138:141], v142 offset:2048
	ds_read_b128 v[142:145], v142 offset:3072
	ds_read_b128 v[146:149], v168
	ds_read_b128 v[150:153], v168 offset:1024
	ds_read_b128 v[164:167], v168 offset:2048
	ds_read_b128 v[168:171], v168 offset:3072
	s_add_i32 m0, s60, 0xc000
	ds_read_b128 v[172:175], v181
	ds_read_b128 v[184:187], v181 offset:1024
	ds_read_b128 v[188:191], v181 offset:2048
	ds_read_b128 v[192:195], v181 offset:3072
	ds_read_b128 v[196:199], v181 offset:4096
	ds_read_b128 v[200:203], v181 offset:5120
	ds_read_b128 v[204:207], v181 offset:6144
	ds_read_b128 v[208:211], v181 offset:7168
	global_load_lds_dwordx4 v160, s[46:47]
	s_add_i32 m0, s60, 0xe000
	s_nop 0
	global_load_lds_dwordx4 v162, s[46:47]
	s_waitcnt vmcnt(8)
	s_waitcnt lgkmcnt(0)
	s_setprio 1
	s_barrier
	v_mfma_f32_16x16x32_bf16 v[126:129], v[130:133], v[172:175], v[126:129]
	v_mfma_f32_16x16x32_bf16 v[122:125], v[138:141], v[172:175], v[122:125]
	v_mfma_f32_16x16x32_bf16 v[110:113], v[130:133], v[188:191], v[110:113]
	v_mfma_f32_16x16x32_bf16 v[106:109], v[138:141], v[188:191], v[106:109]
	v_mfma_f32_16x16x32_bf16 v[94:97], v[130:133], v[196:199], v[94:97]
	v_mfma_f32_16x16x32_bf16 v[90:93], v[138:141], v[196:199], v[90:93]
	v_mfma_f32_16x16x32_bf16 v[78:81], v[130:133], v[204:207], v[78:81]
	v_mfma_f32_16x16x32_bf16 v[74:77], v[138:141], v[204:207], v[74:77]
	v_mfma_f32_16x16x32_bf16 v[126:129], v[134:137], v[184:187], v[126:129]
	v_mfma_f32_16x16x32_bf16 v[122:125], v[142:145], v[184:187], v[122:125]
	v_mfma_f32_16x16x32_bf16 v[110:113], v[134:137], v[192:195], v[110:113]
	v_mfma_f32_16x16x32_bf16 v[106:109], v[142:145], v[192:195], v[106:109]
	v_mfma_f32_16x16x32_bf16 v[94:97], v[134:137], v[200:203], v[94:97]
	v_mfma_f32_16x16x32_bf16 v[90:93], v[142:145], v[200:203], v[90:93]
	v_mfma_f32_16x16x32_bf16 v[78:81], v[134:137], v[208:211], v[78:81]
	v_mfma_f32_16x16x32_bf16 v[74:77], v[142:145], v[208:211], v[74:77]
	s_setprio 0
	s_setprio 1
	v_mfma_f32_16x16x32_bf16 v[118:121], v[146:149], v[172:175], v[118:121]
	v_mfma_f32_16x16x32_bf16 v[114:117], v[164:167], v[172:175], v[114:117]
	v_mfma_f32_16x16x32_bf16 v[102:105], v[146:149], v[188:191], v[102:105]
	v_mfma_f32_16x16x32_bf16 v[98:101], v[164:167], v[188:191], v[98:101]
	v_mfma_f32_16x16x32_bf16 v[86:89], v[146:149], v[196:199], v[86:89]
	v_mfma_f32_16x16x32_bf16 v[82:85], v[164:167], v[196:199], v[82:85]
	v_mfma_f32_16x16x32_bf16 v[70:73], v[146:149], v[204:207], v[70:73]
	v_mfma_f32_16x16x32_bf16 v[66:69], v[164:167], v[204:207], v[66:69]
	v_mfma_f32_16x16x32_bf16 v[118:121], v[150:153], v[184:187], v[118:121]
	v_mfma_f32_16x16x32_bf16 v[114:117], v[168:171], v[184:187], v[114:117]
	v_mfma_f32_16x16x32_bf16 v[102:105], v[150:153], v[192:195], v[102:105]
	v_mfma_f32_16x16x32_bf16 v[98:101], v[168:171], v[192:195], v[98:101]
	v_mfma_f32_16x16x32_bf16 v[86:89], v[150:153], v[200:203], v[86:89]
	v_mfma_f32_16x16x32_bf16 v[82:85], v[168:171], v[200:203], v[82:85]
	v_mfma_f32_16x16x32_bf16 v[70:73], v[150:153], v[208:211], v[70:73]
	v_mfma_f32_16x16x32_bf16 v[66:69], v[168:171], v[208:211], v[66:69]
	s_barrier
	s_setprio 0
	s_add_i32 s24, s24, s57
	v_lshl_add_u64 v[212:213], s[26:27], 0, v[0:1]
	s_mov_b32 m0, s24
	ds_read_b128 v[172:175], v181 offset:16384
	ds_read_b128 v[184:187], v181 offset:17408
	ds_read_b128 v[188:191], v181 offset:18432
	ds_read_b128 v[192:195], v181 offset:19456
	ds_read_b128 v[196:199], v181 offset:20480
	ds_read_b128 v[200:203], v181 offset:21504
	ds_read_b128 v[204:207], v181 offset:22528
	ds_read_b128 v[208:211], v181 offset:23552
	global_load_lds_dwordx4 v[212:213], off
	s_add_i32 m0, s24, 0x2000
	s_add_u32 s50, s26, 0x200000
	v_lshl_add_u64 v[214:215], s[26:27], 0, v[158:159]
	s_addc_u32 s51, s27, 0
	s_add_i32 s24, s49, s57
	global_load_lds_dwordx4 v[214:215], off
	v_lshl_add_u64 v[216:217], s[50:51], 0, v[0:1]
	s_mov_b32 m0, s24
	v_lshl_add_u64 v[218:219], s[22:23], 0, v[156:157]
	global_load_lds_dwordx4 v[216:217], off
	s_add_i32 m0, s24, 0x2000
	s_nop 0
	global_load_lds_dwordx4 v158, s[50:51]
	v_lshl_add_u64 v[216:217], s[22:23], 0, v[154:155]
	s_mov_b32 m0, s60
	s_nop 0
	global_load_lds_dwordx4 v[216:217], off
	s_mov_b32 m0, s61
	s_nop 0
	global_load_lds_dwordx4 v[218:219], off
	s_waitcnt vmcnt(8)
	s_waitcnt lgkmcnt(0)
	s_setprio 1
	s_barrier
	v_mfma_f32_16x16x32_bf16 v[62:65], v[130:133], v[172:175], v[62:65]
	v_mfma_f32_16x16x32_bf16 v[58:61], v[138:141], v[172:175], v[58:61]
	v_mfma_f32_16x16x32_bf16 v[46:49], v[130:133], v[188:191], v[46:49]
	v_mfma_f32_16x16x32_bf16 v[42:45], v[138:141], v[188:191], v[42:45]
	v_mfma_f32_16x16x32_bf16 v[30:33], v[130:133], v[196:199], v[30:33]
	v_mfma_f32_16x16x32_bf16 v[26:29], v[138:141], v[196:199], v[26:29]
	v_mfma_f32_16x16x32_bf16 v[14:17], v[130:133], v[204:207], v[14:17]
	v_mfma_f32_16x16x32_bf16 v[10:13], v[138:141], v[204:207], v[10:13]
	v_mfma_f32_16x16x32_bf16 v[62:65], v[134:137], v[184:187], v[62:65]
	v_mfma_f32_16x16x32_bf16 v[58:61], v[142:145], v[184:187], v[58:61]
	v_mfma_f32_16x16x32_bf16 v[46:49], v[134:137], v[192:195], v[46:49]
	v_mfma_f32_16x16x32_bf16 v[42:45], v[142:145], v[192:195], v[42:45]
	v_mfma_f32_16x16x32_bf16 v[30:33], v[134:137], v[200:203], v[30:33]
	v_mfma_f32_16x16x32_bf16 v[26:29], v[142:145], v[200:203], v[26:29]
	v_mfma_f32_16x16x32_bf16 v[14:17], v[134:137], v[208:211], v[14:17]
	v_mfma_f32_16x16x32_bf16 v[10:13], v[142:145], v[208:211], v[10:13]
	s_setprio 0
	s_setprio 1
	v_mfma_f32_16x16x32_bf16 v[54:57], v[146:149], v[172:175], v[54:57]
	v_mfma_f32_16x16x32_bf16 v[50:53], v[164:167], v[172:175], v[50:53]
	v_mfma_f32_16x16x32_bf16 v[38:41], v[146:149], v[188:191], v[38:41]
	v_mfma_f32_16x16x32_bf16 v[34:37], v[164:167], v[188:191], v[34:37]
	v_mfma_f32_16x16x32_bf16 v[22:25], v[146:149], v[196:199], v[22:25]
	v_mfma_f32_16x16x32_bf16 v[18:21], v[164:167], v[196:199], v[18:21]
	v_mfma_f32_16x16x32_bf16 v[6:9], v[146:149], v[204:207], v[6:9]
	v_mfma_f32_16x16x32_bf16 v[2:5], v[164:167], v[204:207], v[2:5]
	v_mfma_f32_16x16x32_bf16 v[54:57], v[150:153], v[184:187], v[54:57]
	v_mfma_f32_16x16x32_bf16 v[50:53], v[168:171], v[184:187], v[50:53]
	v_mfma_f32_16x16x32_bf16 v[38:41], v[150:153], v[192:195], v[38:41]
	v_mfma_f32_16x16x32_bf16 v[34:37], v[168:171], v[192:195], v[34:37]
	v_mfma_f32_16x16x32_bf16 v[22:25], v[150:153], v[200:203], v[22:25]
	v_mfma_f32_16x16x32_bf16 v[18:21], v[168:171], v[200:203], v[18:21]
	v_mfma_f32_16x16x32_bf16 v[6:9], v[150:153], v[208:211], v[6:9]
	v_mfma_f32_16x16x32_bf16 v[2:5], v[168:171], v[208:211], v[2:5]
	s_barrier
	s_setprio 0
	s_add_i32 s24, 0, 0x18000
	s_add_i32 s49, 0, 0x1c000
	v_add_u32_e32 v142, s24, v177
	v_add_u32_e32 v168, s49, v177
	ds_read_b128 v[130:133], v142
	ds_read_b128 v[134:137], v142 offset:1024
	ds_read_b128 v[138:141], v142 offset:2048
	ds_read_b128 v[142:145], v142 offset:3072
	ds_read_b128 v[146:149], v168
	ds_read_b128 v[150:153], v168 offset:1024
	ds_read_b128 v[164:167], v168 offset:2048
	ds_read_b128 v[168:171], v168 offset:3072
	s_add_u32 s22, s22, 0x200000
	s_addc_u32 s23, s23, 0
	s_mov_b32 m0, s62
	ds_read_b128 v[172:175], v181 offset:32768
	ds_read_b128 v[184:187], v181 offset:33792
	ds_read_b128 v[188:191], v181 offset:34816
	ds_read_b128 v[192:195], v181 offset:35840
	ds_read_b128 v[196:199], v181 offset:36864
	ds_read_b128 v[200:203], v181 offset:37888
	ds_read_b128 v[204:207], v181 offset:38912
	ds_read_b128 v[208:211], v181 offset:39936
	global_load_lds_dwordx4 v154, s[22:23]
	s_mov_b32 m0, s63
	s_nop 0
	global_load_lds_dwordx4 v156, s[22:23]
	s_waitcnt vmcnt(8)
	s_waitcnt lgkmcnt(0)
	s_setprio 1
	s_barrier
	v_mfma_f32_16x16x32_bf16 v[126:129], v[130:133], v[172:175], v[126:129]
	v_mfma_f32_16x16x32_bf16 v[122:125], v[138:141], v[172:175], v[122:125]
	v_mfma_f32_16x16x32_bf16 v[110:113], v[130:133], v[188:191], v[110:113]
	v_mfma_f32_16x16x32_bf16 v[106:109], v[138:141], v[188:191], v[106:109]
	v_mfma_f32_16x16x32_bf16 v[94:97], v[130:133], v[196:199], v[94:97]
	v_mfma_f32_16x16x32_bf16 v[90:93], v[138:141], v[196:199], v[90:93]
	v_mfma_f32_16x16x32_bf16 v[78:81], v[130:133], v[204:207], v[78:81]
	v_mfma_f32_16x16x32_bf16 v[74:77], v[138:141], v[204:207], v[74:77]
	v_mfma_f32_16x16x32_bf16 v[126:129], v[134:137], v[184:187], v[126:129]
	v_mfma_f32_16x16x32_bf16 v[122:125], v[142:145], v[184:187], v[122:125]
	v_mfma_f32_16x16x32_bf16 v[110:113], v[134:137], v[192:195], v[110:113]
	v_mfma_f32_16x16x32_bf16 v[106:109], v[142:145], v[192:195], v[106:109]
	v_mfma_f32_16x16x32_bf16 v[94:97], v[134:137], v[200:203], v[94:97]
	v_mfma_f32_16x16x32_bf16 v[90:93], v[142:145], v[200:203], v[90:93]
	v_mfma_f32_16x16x32_bf16 v[78:81], v[134:137], v[208:211], v[78:81]
	v_mfma_f32_16x16x32_bf16 v[74:77], v[142:145], v[208:211], v[74:77]
	s_setprio 0
	s_setprio 1
	v_mfma_f32_16x16x32_bf16 v[118:121], v[146:149], v[172:175], v[118:121]
	v_mfma_f32_16x16x32_bf16 v[114:117], v[164:167], v[172:175], v[114:117]
	v_mfma_f32_16x16x32_bf16 v[102:105], v[146:149], v[188:191], v[102:105]
	v_mfma_f32_16x16x32_bf16 v[98:101], v[164:167], v[188:191], v[98:101]
	v_mfma_f32_16x16x32_bf16 v[86:89], v[146:149], v[196:199], v[86:89]
	v_mfma_f32_16x16x32_bf16 v[82:85], v[164:167], v[196:199], v[82:85]
	v_mfma_f32_16x16x32_bf16 v[70:73], v[146:149], v[204:207], v[70:73]
	v_mfma_f32_16x16x32_bf16 v[66:69], v[164:167], v[204:207], v[66:69]
	v_mfma_f32_16x16x32_bf16 v[118:121], v[150:153], v[184:187], v[118:121]
	v_mfma_f32_16x16x32_bf16 v[114:117], v[168:171], v[184:187], v[114:117]
	v_mfma_f32_16x16x32_bf16 v[102:105], v[150:153], v[192:195], v[102:105]
	v_mfma_f32_16x16x32_bf16 v[98:101], v[168:171], v[192:195], v[98:101]
	v_mfma_f32_16x16x32_bf16 v[86:89], v[150:153], v[200:203], v[86:89]
	v_mfma_f32_16x16x32_bf16 v[82:85], v[168:171], v[200:203], v[82:85]
	v_mfma_f32_16x16x32_bf16 v[70:73], v[150:153], v[208:211], v[70:73]
	v_mfma_f32_16x16x32_bf16 v[66:69], v[168:171], v[208:211], v[66:69]
	s_barrier
	s_setprio 0
	s_add_i32 s22, s24, s57
	v_lshl_add_u64 v[212:213], v[212:213], 0, s[34:35]
	s_mov_b32 m0, s22
	ds_read_b128 v[172:175], v181 offset:49152
	ds_read_b128 v[184:187], v181 offset:50176
	ds_read_b128 v[188:191], v181 offset:51200
	ds_read_b128 v[192:195], v181 offset:52224
	ds_read_b128 v[196:199], v181 offset:53248
	ds_read_b128 v[200:203], v181 offset:54272
	ds_read_b128 v[204:207], v181 offset:55296
	ds_read_b128 v[208:211], v181 offset:56320
	global_load_lds_dwordx4 v[212:213], off
	s_add_i32 m0, s22, 0x2000
	s_add_u32 s22, s26, 0x200080
	v_lshl_add_u64 v[212:213], v[214:215], 0, s[34:35]
	s_addc_u32 s23, s27, 0
	s_add_i32 s24, s49, s57
	global_load_lds_dwordx4 v[212:213], off
	v_lshl_add_u64 v[212:213], s[22:23], 0, v[0:1]
	s_mov_b32 m0, s24
	s_nop 0
	global_load_lds_dwordx4 v[212:213], off
	s_add_i32 m0, s24, 0x2000
	s_nop 0
	global_load_lds_dwordx4 v158, s[22:23]
	v_lshl_add_u64 v[212:213], v[216:217], 0, s[100:101]
	s_mov_b32 m0, s74
	s_nop 0
	global_load_lds_dwordx4 v[212:213], off
	v_lshl_add_u64 v[212:213], v[218:219], 0, s[100:101]
	s_mov_b32 m0, s75
	s_nop 0
	global_load_lds_dwordx4 v[212:213], off
	s_waitcnt vmcnt(8)
	s_waitcnt lgkmcnt(0)
	s_setprio 1
	s_barrier
	v_mfma_f32_16x16x32_bf16 v[62:65], v[130:133], v[172:175], v[62:65]
	v_mfma_f32_16x16x32_bf16 v[58:61], v[138:141], v[172:175], v[58:61]
	v_mfma_f32_16x16x32_bf16 v[46:49], v[130:133], v[188:191], v[46:49]
	v_mfma_f32_16x16x32_bf16 v[42:45], v[138:141], v[188:191], v[42:45]
	v_mfma_f32_16x16x32_bf16 v[30:33], v[130:133], v[196:199], v[30:33]
	v_mfma_f32_16x16x32_bf16 v[26:29], v[138:141], v[196:199], v[26:29]
	v_mfma_f32_16x16x32_bf16 v[14:17], v[130:133], v[204:207], v[14:17]
	v_mfma_f32_16x16x32_bf16 v[10:13], v[138:141], v[204:207], v[10:13]
	v_mfma_f32_16x16x32_bf16 v[62:65], v[134:137], v[184:187], v[62:65]
	v_mfma_f32_16x16x32_bf16 v[58:61], v[142:145], v[184:187], v[58:61]
	v_mfma_f32_16x16x32_bf16 v[46:49], v[134:137], v[192:195], v[46:49]
	v_mfma_f32_16x16x32_bf16 v[42:45], v[142:145], v[192:195], v[42:45]
	v_mfma_f32_16x16x32_bf16 v[30:33], v[134:137], v[200:203], v[30:33]
	v_mfma_f32_16x16x32_bf16 v[26:29], v[142:145], v[200:203], v[26:29]
	v_mfma_f32_16x16x32_bf16 v[14:17], v[134:137], v[208:211], v[14:17]
	v_mfma_f32_16x16x32_bf16 v[10:13], v[142:145], v[208:211], v[10:13]
	s_setprio 0
	s_setprio 1
	v_mfma_f32_16x16x32_bf16 v[54:57], v[146:149], v[172:175], v[54:57]
	v_mfma_f32_16x16x32_bf16 v[50:53], v[164:167], v[172:175], v[50:53]
	v_mfma_f32_16x16x32_bf16 v[38:41], v[146:149], v[188:191], v[38:41]
	v_mfma_f32_16x16x32_bf16 v[34:37], v[164:167], v[188:191], v[34:37]
	v_mfma_f32_16x16x32_bf16 v[22:25], v[146:149], v[196:199], v[22:25]
	v_mfma_f32_16x16x32_bf16 v[18:21], v[164:167], v[196:199], v[18:21]
	v_mfma_f32_16x16x32_bf16 v[6:9], v[146:149], v[204:207], v[6:9]
	v_mfma_f32_16x16x32_bf16 v[2:5], v[164:167], v[204:207], v[2:5]
	v_mfma_f32_16x16x32_bf16 v[54:57], v[150:153], v[184:187], v[54:57]
	v_mfma_f32_16x16x32_bf16 v[50:53], v[168:171], v[184:187], v[50:53]
	v_mfma_f32_16x16x32_bf16 v[38:41], v[150:153], v[192:195], v[38:41]
	v_mfma_f32_16x16x32_bf16 v[34:37], v[168:171], v[192:195], v[34:37]
	v_mfma_f32_16x16x32_bf16 v[22:25], v[150:153], v[200:203], v[22:25]
	v_mfma_f32_16x16x32_bf16 v[18:21], v[168:171], v[200:203], v[18:21]
	v_mfma_f32_16x16x32_bf16 v[6:9], v[150:153], v[208:211], v[6:9]
	v_mfma_f32_16x16x32_bf16 v[2:5], v[168:171], v[208:211], v[2:5]
	s_barrier
	s_setprio 0
	s_add_i32 s48, s48, 2
	s_add_u32 s46, s46, 0x1000
	s_addc_u32 s47, s47, 0
	s_add_u32 s36, s36, 0x100
	s_addc_u32 s37, s37, 0
	s_cmpk_gt_u32 s48, 0x7d
	s_cbranch_scc0 .LBB0_1004
	s_and_b64 vcc, exec, s[10:11]
	s_cbranch_vccz .LBB0_1007
	s_barrier
